# K-loops: the redundant s_setprio 0 / s_setprio 1 pair in the middle of every MFMA block removed (priority simply stays 1 through the block)
# speedup vs baseline: 1.0003x; 1.0003x over previous
.LBB0_98:
	s_add_u32 s18, s44, 0xfffc0080
	s_addc_u32 s19, s45, -1
	s_add_i32 s46, 0, 0x10000
	s_cmp_eq_u32 s15, 12
	s_cselect_b32 s25, s7, s19
	s_cselect_b32 s24, s10, s18
	s_cselect_b32 s23, s5, s14
	s_cselect_b32 s22, s11, s13
	s_add_i32 s47, 0, 0x14000
	ds_read_b128 v[156:159], v240
	ds_read_b128 v[160:163], v240 offset:1024
	ds_read_b128 v[164:167], v240 offset:2048
	ds_read_b128 v[168:171], v240 offset:3072
	ds_read_b128 v[172:175], v240 offset:16384
	ds_read_b128 v[176:179], v240 offset:17408
	ds_read_b128 v[180:183], v240 offset:18432
	ds_read_b128 v[184:187], v240 offset:19456
	s_add_i32 m0, s29, 0xc000
	ds_read_b128 v[208:211], v155
	ds_read_b128 v[212:215], v155 offset:1024
	ds_read_b128 v[216:219], v155 offset:2048
	ds_read_b128 v[220:223], v155 offset:3072
	ds_read_b128 v[224:227], v155 offset:4096
	ds_read_b128 v[228:231], v155 offset:5120
	ds_read_b128 v[232:235], v155 offset:6144
	ds_read_b128 v[236:239], v155 offset:7168
	global_load_lds_dwordx4 v144, s[44:45]
	s_add_i32 m0, s29, 0xe000
	s_nop 0
	global_load_lds_dwordx4 v146, s[44:45]
	s_waitcnt vmcnt(8)
	s_waitcnt lgkmcnt(0)
	s_barrier
	s_setprio 1
	s_waitcnt lgkmcnt(0)
	v_mfma_f32_16x16x32_bf16 v[128:131], v[156:159], v[208:211], v[128:131]
	v_mfma_f32_16x16x32_bf16 v[120:123], v[164:167], v[208:211], v[120:123]
	v_mfma_f32_16x16x32_bf16 v[112:115], v[156:159], v[216:219], v[112:115]
	v_mfma_f32_16x16x32_bf16 v[104:107], v[164:167], v[216:219], v[104:107]
	v_mfma_f32_16x16x32_bf16 v[96:99], v[156:159], v[224:227], v[96:99]
	v_mfma_f32_16x16x32_bf16 v[88:91], v[164:167], v[224:227], v[88:91]
	v_mfma_f32_16x16x32_bf16 v[80:83], v[156:159], v[232:235], v[80:83]
	v_mfma_f32_16x16x32_bf16 v[72:75], v[164:167], v[232:235], v[72:75]
	v_mfma_f32_16x16x32_bf16 v[128:131], v[160:163], v[212:215], v[128:131]
	v_mfma_f32_16x16x32_bf16 v[120:123], v[168:171], v[212:215], v[120:123]
	v_mfma_f32_16x16x32_bf16 v[112:115], v[160:163], v[220:223], v[112:115]
	v_mfma_f32_16x16x32_bf16 v[104:107], v[168:171], v[220:223], v[104:107]
	v_mfma_f32_16x16x32_bf16 v[96:99], v[160:163], v[228:231], v[96:99]
	v_mfma_f32_16x16x32_bf16 v[88:91], v[168:171], v[228:231], v[88:91]
	v_mfma_f32_16x16x32_bf16 v[80:83], v[160:163], v[236:239], v[80:83]
	v_mfma_f32_16x16x32_bf16 v[72:75], v[168:171], v[236:239], v[72:75]
	v_mfma_f32_16x16x32_bf16 v[124:127], v[172:175], v[208:211], v[124:127]
	v_mfma_f32_16x16x32_bf16 v[116:119], v[180:183], v[208:211], v[116:119]
	v_mfma_f32_16x16x32_bf16 v[108:111], v[172:175], v[216:219], v[108:111]
	v_mfma_f32_16x16x32_bf16 v[100:103], v[180:183], v[216:219], v[100:103]
	v_mfma_f32_16x16x32_bf16 v[92:95], v[172:175], v[224:227], v[92:95]
	v_mfma_f32_16x16x32_bf16 v[84:87], v[180:183], v[224:227], v[84:87]
	v_mfma_f32_16x16x32_bf16 v[76:79], v[172:175], v[232:235], v[76:79]
	v_mfma_f32_16x16x32_bf16 v[68:71], v[180:183], v[232:235], v[68:71]
	v_mfma_f32_16x16x32_bf16 v[124:127], v[176:179], v[212:215], v[124:127]
	v_mfma_f32_16x16x32_bf16 v[116:119], v[184:187], v[212:215], v[116:119]
	v_mfma_f32_16x16x32_bf16 v[108:111], v[176:179], v[220:223], v[108:111]
	v_mfma_f32_16x16x32_bf16 v[100:103], v[184:187], v[220:223], v[100:103]
	v_mfma_f32_16x16x32_bf16 v[92:95], v[176:179], v[228:231], v[92:95]
	v_mfma_f32_16x16x32_bf16 v[84:87], v[184:187], v[228:231], v[84:87]
	v_mfma_f32_16x16x32_bf16 v[76:79], v[176:179], v[236:239], v[76:79]
	v_mfma_f32_16x16x32_bf16 v[68:71], v[184:187], v[236:239], v[68:71]
	s_setprio 0
	s_barrier
	s_add_i32 s18, s46, s28
	s_mov_b32 m0, s18
	ds_read_b128 v[208:211], v155 offset:16384
	ds_read_b128 v[212:215], v155 offset:17408
	ds_read_b128 v[216:219], v155 offset:18432
	ds_read_b128 v[220:223], v155 offset:19456
	ds_read_b128 v[224:227], v155 offset:20480
	ds_read_b128 v[228:231], v155 offset:21504
	ds_read_b128 v[232:235], v155 offset:22528
	ds_read_b128 v[236:239], v155 offset:23552
	global_load_lds_dwordx4 v2, s[22:23]
	s_add_i32 m0, s18, 0x2000
	s_add_u32 s18, s22, 0x40000
	s_addc_u32 s19, s23, 0
	s_add_i32 s46, s47, s28
	global_load_lds_dwordx4 v142, s[22:23]
	s_mov_b32 m0, s46
	s_nop 0
	global_load_lds_dwordx4 v2, s[18:19]
	s_add_i32 m0, s46, 0x2000
	s_nop 0
	global_load_lds_dwordx4 v142, s[18:19]
	s_mov_b32 m0, s29
	s_nop 0
	global_load_lds_dwordx4 v0, s[24:25]
	s_mov_b32 m0, s43
	s_nop 0
	global_load_lds_dwordx4 v140, s[24:25]
	s_waitcnt vmcnt(8)
	s_waitcnt lgkmcnt(0)
	s_barrier
	s_setprio 1
	s_waitcnt lgkmcnt(0)
	v_mfma_f32_16x16x32_bf16 v[64:67], v[156:159], v[208:211], v[64:67]
	v_mfma_f32_16x16x32_bf16 v[56:59], v[164:167], v[208:211], v[56:59]
	v_mfma_f32_16x16x32_bf16 v[48:51], v[156:159], v[216:219], v[48:51]
	v_mfma_f32_16x16x32_bf16 v[40:43], v[164:167], v[216:219], v[40:43]
	v_mfma_f32_16x16x32_bf16 v[32:35], v[156:159], v[224:227], v[32:35]
	v_mfma_f32_16x16x32_bf16 v[24:27], v[164:167], v[224:227], v[24:27]
	v_mfma_f32_16x16x32_bf16 v[16:19], v[156:159], v[232:235], v[16:19]
	v_mfma_f32_16x16x32_bf16 v[8:11], v[164:167], v[232:235], v[8:11]
	v_mfma_f32_16x16x32_bf16 v[64:67], v[160:163], v[212:215], v[64:67]
	v_mfma_f32_16x16x32_bf16 v[56:59], v[168:171], v[212:215], v[56:59]
	v_mfma_f32_16x16x32_bf16 v[48:51], v[160:163], v[220:223], v[48:51]
	v_mfma_f32_16x16x32_bf16 v[40:43], v[168:171], v[220:223], v[40:43]
	v_mfma_f32_16x16x32_bf16 v[32:35], v[160:163], v[228:231], v[32:35]
	v_mfma_f32_16x16x32_bf16 v[24:27], v[168:171], v[228:231], v[24:27]
	v_mfma_f32_16x16x32_bf16 v[16:19], v[160:163], v[236:239], v[16:19]
	v_mfma_f32_16x16x32_bf16 v[8:11], v[168:171], v[236:239], v[8:11]
	v_mfma_f32_16x16x32_bf16 v[60:63], v[172:175], v[208:211], v[60:63]
	v_mfma_f32_16x16x32_bf16 v[52:55], v[180:183], v[208:211], v[52:55]
	v_mfma_f32_16x16x32_bf16 v[44:47], v[172:175], v[216:219], v[44:47]
	v_mfma_f32_16x16x32_bf16 v[36:39], v[180:183], v[216:219], v[36:39]
	v_mfma_f32_16x16x32_bf16 v[28:31], v[172:175], v[224:227], v[28:31]
	v_mfma_f32_16x16x32_bf16 v[20:23], v[180:183], v[224:227], v[20:23]
	v_mfma_f32_16x16x32_bf16 v[12:15], v[172:175], v[232:235], v[12:15]
	v_mfma_f32_16x16x32_bf16 v[4:7], v[180:183], v[232:235], v[4:7]
	v_mfma_f32_16x16x32_bf16 v[60:63], v[176:179], v[212:215], v[60:63]
	v_mfma_f32_16x16x32_bf16 v[52:55], v[184:187], v[212:215], v[52:55]
	v_mfma_f32_16x16x32_bf16 v[44:47], v[176:179], v[220:223], v[44:47]
	v_mfma_f32_16x16x32_bf16 v[36:39], v[184:187], v[220:223], v[36:39]
	v_mfma_f32_16x16x32_bf16 v[28:31], v[176:179], v[228:231], v[28:31]
	v_mfma_f32_16x16x32_bf16 v[20:23], v[184:187], v[228:231], v[20:23]
	v_mfma_f32_16x16x32_bf16 v[12:15], v[176:179], v[236:239], v[12:15]
	v_mfma_f32_16x16x32_bf16 v[4:7], v[184:187], v[236:239], v[4:7]
	s_setprio 0
	s_barrier
	s_add_i32 s46, 0, 0x18000
	s_add_i32 s47, 0, 0x1c000
	ds_read_b128 v[156:159], v240 offset:32768
	ds_read_b128 v[160:163], v240 offset:33792
	ds_read_b128 v[164:167], v240 offset:34816
	ds_read_b128 v[168:171], v240 offset:35840
	ds_read_b128 v[172:175], v240 offset:49152
	ds_read_b128 v[176:179], v240 offset:50176
	ds_read_b128 v[180:183], v240 offset:51200
	ds_read_b128 v[184:187], v240 offset:52224
	s_add_u32 s18, s24, 0x40000
	s_addc_u32 s19, s25, 0
	s_mov_b32 m0, s48
	ds_read_b128 v[208:211], v155 offset:32768
	ds_read_b128 v[212:215], v155 offset:33792
	ds_read_b128 v[216:219], v155 offset:34816
	ds_read_b128 v[220:223], v155 offset:35840
	ds_read_b128 v[224:227], v155 offset:36864
	ds_read_b128 v[228:231], v155 offset:37888
	ds_read_b128 v[232:235], v155 offset:38912
	ds_read_b128 v[236:239], v155 offset:39936
	global_load_lds_dwordx4 v0, s[18:19]
	s_mov_b32 m0, s49
	s_nop 0
	global_load_lds_dwordx4 v140, s[18:19]
	s_waitcnt vmcnt(8)
	s_waitcnt lgkmcnt(0)
	s_barrier
	s_setprio 1
	s_waitcnt lgkmcnt(0)
	v_mfma_f32_16x16x32_bf16 v[128:131], v[156:159], v[208:211], v[128:131]
	v_mfma_f32_16x16x32_bf16 v[120:123], v[164:167], v[208:211], v[120:123]
	v_mfma_f32_16x16x32_bf16 v[112:115], v[156:159], v[216:219], v[112:115]
	v_mfma_f32_16x16x32_bf16 v[104:107], v[164:167], v[216:219], v[104:107]
	v_mfma_f32_16x16x32_bf16 v[96:99], v[156:159], v[224:227], v[96:99]
	v_mfma_f32_16x16x32_bf16 v[88:91], v[164:167], v[224:227], v[88:91]
	v_mfma_f32_16x16x32_bf16 v[80:83], v[156:159], v[232:235], v[80:83]
	v_mfma_f32_16x16x32_bf16 v[72:75], v[164:167], v[232:235], v[72:75]
	v_mfma_f32_16x16x32_bf16 v[128:131], v[160:163], v[212:215], v[128:131]
	v_mfma_f32_16x16x32_bf16 v[120:123], v[168:171], v[212:215], v[120:123]
	v_mfma_f32_16x16x32_bf16 v[112:115], v[160:163], v[220:223], v[112:115]
	v_mfma_f32_16x16x32_bf16 v[104:107], v[168:171], v[220:223], v[104:107]
	v_mfma_f32_16x16x32_bf16 v[96:99], v[160:163], v[228:231], v[96:99]
	v_mfma_f32_16x16x32_bf16 v[88:91], v[168:171], v[228:231], v[88:91]
	v_mfma_f32_16x16x32_bf16 v[80:83], v[160:163], v[236:239], v[80:83]
	v_mfma_f32_16x16x32_bf16 v[72:75], v[168:171], v[236:239], v[72:75]
	v_mfma_f32_16x16x32_bf16 v[124:127], v[172:175], v[208:211], v[124:127]
	v_mfma_f32_16x16x32_bf16 v[116:119], v[180:183], v[208:211], v[116:119]
	v_mfma_f32_16x16x32_bf16 v[108:111], v[172:175], v[216:219], v[108:111]
	v_mfma_f32_16x16x32_bf16 v[100:103], v[180:183], v[216:219], v[100:103]
	v_mfma_f32_16x16x32_bf16 v[92:95], v[172:175], v[224:227], v[92:95]
	v_mfma_f32_16x16x32_bf16 v[84:87], v[180:183], v[224:227], v[84:87]
	v_mfma_f32_16x16x32_bf16 v[76:79], v[172:175], v[232:235], v[76:79]
	v_mfma_f32_16x16x32_bf16 v[68:71], v[180:183], v[232:235], v[68:71]
	v_mfma_f32_16x16x32_bf16 v[124:127], v[176:179], v[212:215], v[124:127]
	v_mfma_f32_16x16x32_bf16 v[116:119], v[184:187], v[212:215], v[116:119]
	v_mfma_f32_16x16x32_bf16 v[108:111], v[176:179], v[220:223], v[108:111]
	v_mfma_f32_16x16x32_bf16 v[100:103], v[184:187], v[220:223], v[100:103]
	v_mfma_f32_16x16x32_bf16 v[92:95], v[176:179], v[228:231], v[92:95]
	v_mfma_f32_16x16x32_bf16 v[84:87], v[184:187], v[228:231], v[84:87]
	v_mfma_f32_16x16x32_bf16 v[76:79], v[176:179], v[236:239], v[76:79]
	v_mfma_f32_16x16x32_bf16 v[68:71], v[184:187], v[236:239], v[68:71]
	s_setprio 0
	s_barrier
	s_add_i32 s18, s46, s28
	s_add_u32 s100, s22, 0x80
	s_addc_u32 s101, s23, 0
	s_mov_b32 m0, s18
	ds_read_b128 v[208:211], v155 offset:49152
	ds_read_b128 v[212:215], v155 offset:50176
	ds_read_b128 v[216:219], v155 offset:51200
	ds_read_b128 v[220:223], v155 offset:52224
	ds_read_b128 v[224:227], v155 offset:53248
	ds_read_b128 v[228:231], v155 offset:54272
	ds_read_b128 v[232:235], v155 offset:55296
	ds_read_b128 v[236:239], v155 offset:56320
	global_load_lds_dwordx4 v2, s[100:101]
	s_add_i32 m0, s18, 0x2000
	s_add_u32 s18, s22, 0x40080
	s_addc_u32 s19, s23, 0
	s_add_i32 s22, s47, s28
	global_load_lds_dwordx4 v142, s[100:101]
	s_mov_b32 m0, s22
	s_nop 0
	global_load_lds_dwordx4 v2, s[18:19]
	s_add_i32 m0, s22, 0x2000
	s_nop 0
	global_load_lds_dwordx4 v142, s[18:19]
	s_add_u32 s100, s24, 0x80
	s_addc_u32 s101, s25, 0
	s_mov_b32 m0, s50
	s_nop 0
	global_load_lds_dwordx4 v0, s[100:101]
	s_mov_b32 m0, s51
	s_nop 0
	global_load_lds_dwordx4 v140, s[100:101]
	s_waitcnt vmcnt(8)
	s_waitcnt lgkmcnt(0)
	s_barrier
	s_setprio 1
	s_waitcnt lgkmcnt(0)
	v_mfma_f32_16x16x32_bf16 v[64:67], v[156:159], v[208:211], v[64:67]
	v_mfma_f32_16x16x32_bf16 v[56:59], v[164:167], v[208:211], v[56:59]
	v_mfma_f32_16x16x32_bf16 v[48:51], v[156:159], v[216:219], v[48:51]
	v_mfma_f32_16x16x32_bf16 v[40:43], v[164:167], v[216:219], v[40:43]
	v_mfma_f32_16x16x32_bf16 v[32:35], v[156:159], v[224:227], v[32:35]
	v_mfma_f32_16x16x32_bf16 v[24:27], v[164:167], v[224:227], v[24:27]
	v_mfma_f32_16x16x32_bf16 v[16:19], v[156:159], v[232:235], v[16:19]
	v_mfma_f32_16x16x32_bf16 v[8:11], v[164:167], v[232:235], v[8:11]
	v_mfma_f32_16x16x32_bf16 v[64:67], v[160:163], v[212:215], v[64:67]
	v_mfma_f32_16x16x32_bf16 v[56:59], v[168:171], v[212:215], v[56:59]
	v_mfma_f32_16x16x32_bf16 v[48:51], v[160:163], v[220:223], v[48:51]
	v_mfma_f32_16x16x32_bf16 v[40:43], v[168:171], v[220:223], v[40:43]
	v_mfma_f32_16x16x32_bf16 v[32:35], v[160:163], v[228:231], v[32:35]
	v_mfma_f32_16x16x32_bf16 v[24:27], v[168:171], v[228:231], v[24:27]
	v_mfma_f32_16x16x32_bf16 v[16:19], v[160:163], v[236:239], v[16:19]
	v_mfma_f32_16x16x32_bf16 v[8:11], v[168:171], v[236:239], v[8:11]
	v_mfma_f32_16x16x32_bf16 v[60:63], v[172:175], v[208:211], v[60:63]
	v_mfma_f32_16x16x32_bf16 v[52:55], v[180:183], v[208:211], v[52:55]
	v_mfma_f32_16x16x32_bf16 v[44:47], v[172:175], v[216:219], v[44:47]
	v_mfma_f32_16x16x32_bf16 v[36:39], v[180:183], v[216:219], v[36:39]
	v_mfma_f32_16x16x32_bf16 v[28:31], v[172:175], v[224:227], v[28:31]
	v_mfma_f32_16x16x32_bf16 v[20:23], v[180:183], v[224:227], v[20:23]
	v_mfma_f32_16x16x32_bf16 v[12:15], v[172:175], v[232:235], v[12:15]
	v_mfma_f32_16x16x32_bf16 v[4:7], v[180:183], v[232:235], v[4:7]
	v_mfma_f32_16x16x32_bf16 v[60:63], v[176:179], v[212:215], v[60:63]
	v_mfma_f32_16x16x32_bf16 v[52:55], v[184:187], v[212:215], v[52:55]
	v_mfma_f32_16x16x32_bf16 v[44:47], v[176:179], v[220:223], v[44:47]
	v_mfma_f32_16x16x32_bf16 v[36:39], v[184:187], v[220:223], v[36:39]
	v_mfma_f32_16x16x32_bf16 v[28:31], v[176:179], v[228:231], v[28:31]
	v_mfma_f32_16x16x32_bf16 v[20:23], v[184:187], v[228:231], v[20:23]
	v_mfma_f32_16x16x32_bf16 v[12:15], v[176:179], v[236:239], v[12:15]
	v_mfma_f32_16x16x32_bf16 v[4:7], v[184:187], v[236:239], v[4:7]
	s_setprio 0
	s_barrier
	s_add_i32 s15, s15, 2
	s_add_u32 s44, s44, 0x100
	s_addc_u32 s45, s45, 0
	s_add_u32 s13, s13, 0x100
	s_addc_u32 s14, s14, 0
	s_cmp_gt_u32 s15, 13
	s_cbranch_scc0 .LBB0_98
	s_lshl_b32 s5, s42, 8
	s_and_b64 vcc, exec, s[2:3]
	s_cbranch_vccz .LBB0_101
	v_or_b32_e32 v148, s5, v152
	v_ashrrev_i32_e32 v149, 31, v148
	v_readlane_b32 s10, v255, 11
	v_lshlrev_b64 v[148:149], 6, v[148:149]
	v_readlane_b32 s11, v255, 12
	s_nop 1
	v_lshl_add_u64 v[148:149], s[10:11], 0, v[148:149]
	global_load_dwordx4 v[156:159], v[148:149], off
	global_load_dwordx4 v[160:163], v[148:149], off offset:32
	global_load_dwordx4 v[164:167], v[148:149], off offset:16
	global_load_dwordx4 v[168:171], v[148:149], off offset:48
	s_barrier

.LBB0_504:
	s_add_u32 s10, s16, s44
	s_addc_u32 s11, s17, s45
	s_add_u32 s10, s10, 0x100
	s_addc_u32 s11, s11, 0
	s_add_u32 s18, s13, s44
	s_addc_u32 s19, s14, s45
	s_cmpk_eq_i32 s44, 0xb00
	s_cselect_b32 s25, s5, s11
	s_cselect_b32 s24, s4, s10
	s_cselect_b32 s23, s7, s19
	s_cselect_b32 s22, s6, s18
	s_add_i32 s10, 0, 0x10000
	v_add_u32_e32 v0, s10, v208
	s_add_i32 s18, 0, 0x14000
	ds_read_b128 v[162:165], v0
	ds_read_b128 v[166:169], v0 offset:1024
	ds_read_b128 v[170:173], v0 offset:2048
	ds_read_b128 v[174:177], v0 offset:3072
	v_add_u32_e32 v0, s18, v208
	ds_read_b128 v[178:181], v0
	ds_read_b128 v[182:185], v0 offset:1024
	ds_read_b128 v[212:215], v0 offset:2048
	ds_read_b128 v[216:219], v0 offset:3072
	v_lshl_add_u64 v[0:1], v[158:159], 0, s[44:45]
	s_add_i32 m0, s47, 0xc000
	ds_read_b128 v[220:223], v211
	ds_read_b128 v[224:227], v211 offset:1024
	ds_read_b128 v[228:231], v211 offset:2048
	ds_read_b128 v[232:235], v211 offset:3072
	ds_read_b128 v[236:239], v211 offset:4096
	ds_read_b128 v[240:243], v211 offset:5120
	ds_read_b128 v[244:247], v211 offset:6144
	ds_read_b128 v[248:251], v211 offset:7168
	global_load_lds_dwordx4 v[0:1], off
	v_lshl_add_u64 v[0:1], v[160:161], 0, s[44:45]
	s_add_i32 m0, s47, 0xe000
	s_nop 0
	global_load_lds_dwordx4 v[0:1], off
	s_waitcnt vmcnt(8)
	s_waitcnt lgkmcnt(0)
	s_barrier
	s_setprio 1
	s_waitcnt lgkmcnt(0)
	v_mfma_f32_16x16x32_bf16 v[128:131], v[162:165], v[220:223], v[128:131]
	v_mfma_f32_16x16x32_bf16 v[124:127], v[170:173], v[220:223], v[124:127]
	v_mfma_f32_16x16x32_bf16 v[112:115], v[162:165], v[228:231], v[112:115]
	v_mfma_f32_16x16x32_bf16 v[108:111], v[170:173], v[228:231], v[108:111]
	v_mfma_f32_16x16x32_bf16 v[96:99], v[162:165], v[236:239], v[96:99]
	v_mfma_f32_16x16x32_bf16 v[92:95], v[170:173], v[236:239], v[92:95]
	v_mfma_f32_16x16x32_bf16 v[80:83], v[162:165], v[244:247], v[80:83]
	v_mfma_f32_16x16x32_bf16 v[76:79], v[170:173], v[244:247], v[76:79]
	v_mfma_f32_16x16x32_bf16 v[128:131], v[166:169], v[224:227], v[128:131]
	v_mfma_f32_16x16x32_bf16 v[124:127], v[174:177], v[224:227], v[124:127]
	v_mfma_f32_16x16x32_bf16 v[112:115], v[166:169], v[232:235], v[112:115]
	v_mfma_f32_16x16x32_bf16 v[108:111], v[174:177], v[232:235], v[108:111]
	v_mfma_f32_16x16x32_bf16 v[96:99], v[166:169], v[240:243], v[96:99]
	v_mfma_f32_16x16x32_bf16 v[92:95], v[174:177], v[240:243], v[92:95]
	v_mfma_f32_16x16x32_bf16 v[80:83], v[166:169], v[248:251], v[80:83]
	v_mfma_f32_16x16x32_bf16 v[76:79], v[174:177], v[248:251], v[76:79]
	v_mfma_f32_16x16x32_bf16 v[120:123], v[178:181], v[220:223], v[120:123]
	v_mfma_f32_16x16x32_bf16 v[116:119], v[212:215], v[220:223], v[116:119]
	v_mfma_f32_16x16x32_bf16 v[104:107], v[178:181], v[228:231], v[104:107]
	v_mfma_f32_16x16x32_bf16 v[100:103], v[212:215], v[228:231], v[100:103]
	v_mfma_f32_16x16x32_bf16 v[88:91], v[178:181], v[236:239], v[88:91]
	v_mfma_f32_16x16x32_bf16 v[84:87], v[212:215], v[236:239], v[84:87]
	v_mfma_f32_16x16x32_bf16 v[72:75], v[178:181], v[244:247], v[72:75]
	v_mfma_f32_16x16x32_bf16 v[68:71], v[212:215], v[244:247], v[68:71]
	v_mfma_f32_16x16x32_bf16 v[120:123], v[182:185], v[224:227], v[120:123]
	v_mfma_f32_16x16x32_bf16 v[116:119], v[216:219], v[224:227], v[116:119]
	v_mfma_f32_16x16x32_bf16 v[104:107], v[182:185], v[232:235], v[104:107]
	v_mfma_f32_16x16x32_bf16 v[100:103], v[216:219], v[232:235], v[100:103]
	v_mfma_f32_16x16x32_bf16 v[88:91], v[182:185], v[240:243], v[88:91]
	v_mfma_f32_16x16x32_bf16 v[84:87], v[216:219], v[240:243], v[84:87]
	v_mfma_f32_16x16x32_bf16 v[72:75], v[182:185], v[248:251], v[72:75]
	v_mfma_f32_16x16x32_bf16 v[68:71], v[216:219], v[248:251], v[68:71]
	s_setprio 0
	s_barrier
	s_add_i32 s10, s10, s46
	s_mov_b32 m0, s10
	ds_read_b128 v[220:223], v211 offset:16384
	ds_read_b128 v[224:227], v211 offset:17408
	ds_read_b128 v[228:231], v211 offset:18432
	ds_read_b128 v[232:235], v211 offset:19456
	ds_read_b128 v[236:239], v211 offset:20480
	ds_read_b128 v[240:243], v211 offset:21504
	ds_read_b128 v[244:247], v211 offset:22528
	ds_read_b128 v[248:251], v211 offset:23552
	global_load_lds_dwordx4 v140, s[22:23]
	s_add_i32 m0, s10, 0x2000
	s_add_u32 s10, s22, 0x60000
	s_addc_u32 s11, s23, 0
	s_add_i32 s18, s18, s46
	global_load_lds_dwordx4 v142, s[22:23]
	s_mov_b32 m0, s18
	s_nop 0
	global_load_lds_dwordx4 v140, s[10:11]
	s_add_i32 m0, s18, 0x2000
	s_nop 0
	global_load_lds_dwordx4 v142, s[10:11]
	s_mov_b32 m0, s47
	s_nop 0
	global_load_lds_dwordx4 v140, s[24:25]
	s_mov_b32 m0, s48
	s_nop 0
	global_load_lds_dwordx4 v142, s[24:25]
	s_waitcnt vmcnt(8)
	s_waitcnt lgkmcnt(0)
	s_barrier
	s_setprio 1
	s_waitcnt lgkmcnt(0)
	v_mfma_f32_16x16x32_bf16 v[64:67], v[162:165], v[220:223], v[64:67]
	v_mfma_f32_16x16x32_bf16 v[60:63], v[170:173], v[220:223], v[60:63]
	v_mfma_f32_16x16x32_bf16 v[48:51], v[162:165], v[228:231], v[48:51]
	v_mfma_f32_16x16x32_bf16 v[44:47], v[170:173], v[228:231], v[44:47]
	v_mfma_f32_16x16x32_bf16 v[32:35], v[162:165], v[236:239], v[32:35]
	v_mfma_f32_16x16x32_bf16 v[28:31], v[170:173], v[236:239], v[28:31]
	v_mfma_f32_16x16x32_bf16 v[16:19], v[162:165], v[244:247], v[16:19]
	v_mfma_f32_16x16x32_bf16 v[12:15], v[170:173], v[244:247], v[12:15]
	v_mfma_f32_16x16x32_bf16 v[64:67], v[166:169], v[224:227], v[64:67]
	v_mfma_f32_16x16x32_bf16 v[60:63], v[174:177], v[224:227], v[60:63]
	v_mfma_f32_16x16x32_bf16 v[48:51], v[166:169], v[232:235], v[48:51]
	v_mfma_f32_16x16x32_bf16 v[44:47], v[174:177], v[232:235], v[44:47]
	v_mfma_f32_16x16x32_bf16 v[32:35], v[166:169], v[240:243], v[32:35]
	v_mfma_f32_16x16x32_bf16 v[28:31], v[174:177], v[240:243], v[28:31]
	v_mfma_f32_16x16x32_bf16 v[16:19], v[166:169], v[248:251], v[16:19]
	v_mfma_f32_16x16x32_bf16 v[12:15], v[174:177], v[248:251], v[12:15]
	v_mfma_f32_16x16x32_bf16 v[56:59], v[178:181], v[220:223], v[56:59]
	v_mfma_f32_16x16x32_bf16 v[52:55], v[212:215], v[220:223], v[52:55]
	v_mfma_f32_16x16x32_bf16 v[40:43], v[178:181], v[228:231], v[40:43]
	v_mfma_f32_16x16x32_bf16 v[36:39], v[212:215], v[228:231], v[36:39]
	v_mfma_f32_16x16x32_bf16 v[24:27], v[178:181], v[236:239], v[24:27]
	v_mfma_f32_16x16x32_bf16 v[20:23], v[212:215], v[236:239], v[20:23]
	v_mfma_f32_16x16x32_bf16 v[8:11], v[178:181], v[244:247], v[8:11]
	v_mfma_f32_16x16x32_bf16 v[4:7], v[212:215], v[244:247], v[4:7]
	v_mfma_f32_16x16x32_bf16 v[56:59], v[182:185], v[224:227], v[56:59]
	v_mfma_f32_16x16x32_bf16 v[52:55], v[216:219], v[224:227], v[52:55]
	v_mfma_f32_16x16x32_bf16 v[40:43], v[182:185], v[232:235], v[40:43]
	v_mfma_f32_16x16x32_bf16 v[36:39], v[216:219], v[232:235], v[36:39]
	v_mfma_f32_16x16x32_bf16 v[24:27], v[182:185], v[240:243], v[24:27]
	v_mfma_f32_16x16x32_bf16 v[20:23], v[216:219], v[240:243], v[20:23]
	v_mfma_f32_16x16x32_bf16 v[8:11], v[182:185], v[248:251], v[8:11]
	v_mfma_f32_16x16x32_bf16 v[4:7], v[216:219], v[248:251], v[4:7]
	s_setprio 0
	s_barrier
	s_add_i32 s18, 0, 0x18000
	v_add_u32_e32 v2, s18, v208
	s_add_i32 s19, 0, 0x1c000
	ds_read_b128 v[162:165], v2
	ds_read_b128 v[166:169], v2 offset:1024
	ds_read_b128 v[170:173], v2 offset:2048
	ds_read_b128 v[174:177], v2 offset:3072
	v_add_u32_e32 v2, s19, v208
	ds_read_b128 v[178:181], v2
	ds_read_b128 v[182:185], v2 offset:1024
	ds_read_b128 v[212:215], v2 offset:2048
	ds_read_b128 v[216:219], v2 offset:3072
	s_add_u32 s10, s24, 0x60000
	s_addc_u32 s11, s25, 0
	s_mov_b32 m0, s49
	ds_read_b128 v[220:223], v211 offset:32768
	ds_read_b128 v[224:227], v211 offset:33792
	ds_read_b128 v[228:231], v211 offset:34816
	ds_read_b128 v[232:235], v211 offset:35840
	ds_read_b128 v[236:239], v211 offset:36864
	ds_read_b128 v[240:243], v211 offset:37888
	ds_read_b128 v[244:247], v211 offset:38912
	ds_read_b128 v[248:251], v211 offset:39936
	global_load_lds_dwordx4 v140, s[10:11]
	s_mov_b32 m0, s50
	s_nop 0
	global_load_lds_dwordx4 v142, s[10:11]
	s_waitcnt vmcnt(8)
	s_waitcnt lgkmcnt(0)
	s_barrier
	s_setprio 1
	s_waitcnt lgkmcnt(0)
	v_mfma_f32_16x16x32_bf16 v[128:131], v[162:165], v[220:223], v[128:131]
	v_mfma_f32_16x16x32_bf16 v[124:127], v[170:173], v[220:223], v[124:127]
	v_mfma_f32_16x16x32_bf16 v[112:115], v[162:165], v[228:231], v[112:115]
	v_mfma_f32_16x16x32_bf16 v[108:111], v[170:173], v[228:231], v[108:111]
	v_mfma_f32_16x16x32_bf16 v[96:99], v[162:165], v[236:239], v[96:99]
	v_mfma_f32_16x16x32_bf16 v[92:95], v[170:173], v[236:239], v[92:95]
	v_mfma_f32_16x16x32_bf16 v[80:83], v[162:165], v[244:247], v[80:83]
	v_mfma_f32_16x16x32_bf16 v[76:79], v[170:173], v[244:247], v[76:79]
	v_mfma_f32_16x16x32_bf16 v[128:131], v[166:169], v[224:227], v[128:131]
	v_mfma_f32_16x16x32_bf16 v[124:127], v[174:177], v[224:227], v[124:127]
	v_mfma_f32_16x16x32_bf16 v[112:115], v[166:169], v[232:235], v[112:115]
	v_mfma_f32_16x16x32_bf16 v[108:111], v[174:177], v[232:235], v[108:111]
	v_mfma_f32_16x16x32_bf16 v[96:99], v[166:169], v[240:243], v[96:99]
	v_mfma_f32_16x16x32_bf16 v[92:95], v[174:177], v[240:243], v[92:95]
	v_mfma_f32_16x16x32_bf16 v[80:83], v[166:169], v[248:251], v[80:83]
	v_mfma_f32_16x16x32_bf16 v[76:79], v[174:177], v[248:251], v[76:79]
	v_mfma_f32_16x16x32_bf16 v[120:123], v[178:181], v[220:223], v[120:123]
	v_mfma_f32_16x16x32_bf16 v[116:119], v[212:215], v[220:223], v[116:119]
	v_mfma_f32_16x16x32_bf16 v[104:107], v[178:181], v[228:231], v[104:107]
	v_mfma_f32_16x16x32_bf16 v[100:103], v[212:215], v[228:231], v[100:103]
	v_mfma_f32_16x16x32_bf16 v[88:91], v[178:181], v[236:239], v[88:91]
	v_mfma_f32_16x16x32_bf16 v[84:87], v[212:215], v[236:239], v[84:87]
	v_mfma_f32_16x16x32_bf16 v[72:75], v[178:181], v[244:247], v[72:75]
	v_mfma_f32_16x16x32_bf16 v[68:71], v[212:215], v[244:247], v[68:71]
	v_mfma_f32_16x16x32_bf16 v[120:123], v[182:185], v[224:227], v[120:123]
	v_mfma_f32_16x16x32_bf16 v[116:119], v[216:219], v[224:227], v[116:119]
	v_mfma_f32_16x16x32_bf16 v[104:107], v[182:185], v[232:235], v[104:107]
	v_mfma_f32_16x16x32_bf16 v[100:103], v[216:219], v[232:235], v[100:103]
	v_mfma_f32_16x16x32_bf16 v[88:91], v[182:185], v[240:243], v[88:91]
	v_mfma_f32_16x16x32_bf16 v[84:87], v[216:219], v[240:243], v[84:87]
	v_mfma_f32_16x16x32_bf16 v[72:75], v[182:185], v[248:251], v[72:75]
	v_mfma_f32_16x16x32_bf16 v[68:71], v[216:219], v[248:251], v[68:71]
	s_setprio 0
	s_barrier
	s_add_i32 s10, s18, s46
	s_add_u32 s100, s22, 0x80
	s_addc_u32 s101, s23, 0
	s_mov_b32 m0, s10
	ds_read_b128 v[220:223], v211 offset:49152
	ds_read_b128 v[224:227], v211 offset:50176
	ds_read_b128 v[228:231], v211 offset:51200
	ds_read_b128 v[232:235], v211 offset:52224
	ds_read_b128 v[236:239], v211 offset:53248
	ds_read_b128 v[240:243], v211 offset:54272
	ds_read_b128 v[244:247], v211 offset:55296
	ds_read_b128 v[248:251], v211 offset:56320
	global_load_lds_dwordx4 v140, s[100:101]
	s_add_i32 m0, s10, 0x2000
	s_add_u32 s10, s22, 0x60080
	s_addc_u32 s11, s23, 0
	s_add_i32 s18, s19, s46
	global_load_lds_dwordx4 v142, s[100:101]
	s_mov_b32 m0, s18
	s_nop 0
	global_load_lds_dwordx4 v140, s[10:11]
	s_add_i32 m0, s18, 0x2000
	s_nop 0
	global_load_lds_dwordx4 v142, s[10:11]
	s_add_u32 s100, s24, 0x80
	s_addc_u32 s101, s25, 0
	s_mov_b32 m0, s52
	s_nop 0
	global_load_lds_dwordx4 v140, s[100:101]
	s_mov_b32 m0, s53
	s_nop 0
	global_load_lds_dwordx4 v142, s[100:101]
	s_waitcnt vmcnt(8)
	s_waitcnt lgkmcnt(0)
	s_barrier
	s_setprio 1
	s_waitcnt lgkmcnt(0)
	v_mfma_f32_16x16x32_bf16 v[64:67], v[162:165], v[220:223], v[64:67]
	v_mfma_f32_16x16x32_bf16 v[60:63], v[170:173], v[220:223], v[60:63]
	v_mfma_f32_16x16x32_bf16 v[48:51], v[162:165], v[228:231], v[48:51]
	v_mfma_f32_16x16x32_bf16 v[44:47], v[170:173], v[228:231], v[44:47]
	v_mfma_f32_16x16x32_bf16 v[32:35], v[162:165], v[236:239], v[32:35]
	v_mfma_f32_16x16x32_bf16 v[28:31], v[170:173], v[236:239], v[28:31]
	v_mfma_f32_16x16x32_bf16 v[16:19], v[162:165], v[244:247], v[16:19]
	v_mfma_f32_16x16x32_bf16 v[12:15], v[170:173], v[244:247], v[12:15]
	v_mfma_f32_16x16x32_bf16 v[64:67], v[166:169], v[224:227], v[64:67]
	v_mfma_f32_16x16x32_bf16 v[60:63], v[174:177], v[224:227], v[60:63]
	v_mfma_f32_16x16x32_bf16 v[48:51], v[166:169], v[232:235], v[48:51]
	v_mfma_f32_16x16x32_bf16 v[44:47], v[174:177], v[232:235], v[44:47]
	v_mfma_f32_16x16x32_bf16 v[32:35], v[166:169], v[240:243], v[32:35]
	v_mfma_f32_16x16x32_bf16 v[28:31], v[174:177], v[240:243], v[28:31]
	v_mfma_f32_16x16x32_bf16 v[16:19], v[166:169], v[248:251], v[16:19]
	v_mfma_f32_16x16x32_bf16 v[12:15], v[174:177], v[248:251], v[12:15]
	v_mfma_f32_16x16x32_bf16 v[56:59], v[178:181], v[220:223], v[56:59]
	v_mfma_f32_16x16x32_bf16 v[52:55], v[212:215], v[220:223], v[52:55]
	v_mfma_f32_16x16x32_bf16 v[40:43], v[178:181], v[228:231], v[40:43]
	v_mfma_f32_16x16x32_bf16 v[36:39], v[212:215], v[228:231], v[36:39]
	v_mfma_f32_16x16x32_bf16 v[24:27], v[178:181], v[236:239], v[24:27]
	v_mfma_f32_16x16x32_bf16 v[20:23], v[212:215], v[236:239], v[20:23]
	v_mfma_f32_16x16x32_bf16 v[8:11], v[178:181], v[244:247], v[8:11]
	v_mfma_f32_16x16x32_bf16 v[4:7], v[212:215], v[244:247], v[4:7]
	v_mfma_f32_16x16x32_bf16 v[56:59], v[182:185], v[224:227], v[56:59]
	v_mfma_f32_16x16x32_bf16 v[52:55], v[216:219], v[224:227], v[52:55]
	v_mfma_f32_16x16x32_bf16 v[40:43], v[182:185], v[232:235], v[40:43]
	v_mfma_f32_16x16x32_bf16 v[36:39], v[216:219], v[232:235], v[36:39]
	v_mfma_f32_16x16x32_bf16 v[24:27], v[182:185], v[240:243], v[24:27]
	v_mfma_f32_16x16x32_bf16 v[20:23], v[216:219], v[240:243], v[20:23]
	v_mfma_f32_16x16x32_bf16 v[8:11], v[182:185], v[248:251], v[8:11]
	v_mfma_f32_16x16x32_bf16 v[4:7], v[216:219], v[248:251], v[4:7]
	s_setprio 0
	s_barrier
	s_add_i32 s10, s15, 2
	s_add_u32 s44, s44, 0x100
	s_addc_u32 s45, s45, 0
	s_cmp_gt_u32 s15, 21
	s_cbranch_scc1 .LBB0_513
	s_mov_b32 s15, s10
	s_cmp_lt_i32 s15, 16
	s_cbranch_scc1 .LBB0_490

.LBB0_811:
	s_add_u32 s42, s44, 0x100
	s_addc_u32 s43, s45, 0
	s_add_i32 s18, 0, 0x10000
	s_cmp_eq_u32 s15, 40
	s_cselect_b32 s25, s11, s43
	s_cselect_b32 s24, s10, s42
	s_cselect_b32 s23, s17, s14
	s_cselect_b32 s22, s16, s13
	s_add_i32 s62, 0, 0x14000
	ds_read_b128 v[144:147], v213
	ds_read_b128 v[148:151], v213 offset:1024
	ds_read_b128 v[152:155], v213 offset:2048
	ds_read_b128 v[156:159], v213 offset:3072
	ds_read_b128 v[160:163], v213 offset:16384
	ds_read_b128 v[164:167], v213 offset:17408
	ds_read_b128 v[168:171], v213 offset:18432
	ds_read_b128 v[172:175], v213 offset:19456
	s_add_i32 m0, s47, 0xc000
	ds_read_b128 v[176:179], v212
	ds_read_b128 v[180:183], v212 offset:1024
	ds_read_b128 v[184:187], v212 offset:2048
	ds_read_b128 v[214:217], v212 offset:3072
	ds_read_b128 v[218:221], v212 offset:4096
	ds_read_b128 v[222:225], v212 offset:5120
	ds_read_b128 v[226:229], v212 offset:6144
	ds_read_b128 v[230:233], v212 offset:7168
	global_load_lds_dwordx4 v140, s[44:45]
	s_add_i32 m0, s47, 0xe000
	s_nop 0
	global_load_lds_dwordx4 v142, s[44:45]
	s_waitcnt vmcnt(8)
	s_waitcnt lgkmcnt(0)
	s_barrier
	s_setprio 1
	s_waitcnt lgkmcnt(0)
	v_mfma_f32_16x16x32_bf16 v[128:131], v[144:147], v[176:179], v[128:131]
	v_mfma_f32_16x16x32_bf16 v[124:127], v[152:155], v[176:179], v[124:127]
	v_mfma_f32_16x16x32_bf16 v[112:115], v[144:147], v[184:187], v[112:115]
	v_mfma_f32_16x16x32_bf16 v[108:111], v[152:155], v[184:187], v[108:111]
	v_mfma_f32_16x16x32_bf16 v[96:99], v[144:147], v[218:221], v[96:99]
	v_mfma_f32_16x16x32_bf16 v[92:95], v[152:155], v[218:221], v[92:95]
	v_mfma_f32_16x16x32_bf16 v[80:83], v[144:147], v[226:229], v[80:83]
	v_mfma_f32_16x16x32_bf16 v[76:79], v[152:155], v[226:229], v[76:79]
	v_mfma_f32_16x16x32_bf16 v[128:131], v[148:151], v[180:183], v[128:131]
	v_mfma_f32_16x16x32_bf16 v[124:127], v[156:159], v[180:183], v[124:127]
	v_mfma_f32_16x16x32_bf16 v[112:115], v[148:151], v[214:217], v[112:115]
	v_mfma_f32_16x16x32_bf16 v[108:111], v[156:159], v[214:217], v[108:111]
	v_mfma_f32_16x16x32_bf16 v[96:99], v[148:151], v[222:225], v[96:99]
	v_mfma_f32_16x16x32_bf16 v[92:95], v[156:159], v[222:225], v[92:95]
	v_mfma_f32_16x16x32_bf16 v[80:83], v[148:151], v[230:233], v[80:83]
	v_mfma_f32_16x16x32_bf16 v[76:79], v[156:159], v[230:233], v[76:79]
	v_mfma_f32_16x16x32_bf16 v[120:123], v[160:163], v[176:179], v[120:123]
	v_mfma_f32_16x16x32_bf16 v[116:119], v[168:171], v[176:179], v[116:119]
	v_mfma_f32_16x16x32_bf16 v[104:107], v[160:163], v[184:187], v[104:107]
	v_mfma_f32_16x16x32_bf16 v[100:103], v[168:171], v[184:187], v[100:103]
	v_mfma_f32_16x16x32_bf16 v[88:91], v[160:163], v[218:221], v[88:91]
	v_mfma_f32_16x16x32_bf16 v[84:87], v[168:171], v[218:221], v[84:87]
	v_mfma_f32_16x16x32_bf16 v[72:75], v[160:163], v[226:229], v[72:75]
	v_mfma_f32_16x16x32_bf16 v[68:71], v[168:171], v[226:229], v[68:71]
	v_mfma_f32_16x16x32_bf16 v[120:123], v[164:167], v[180:183], v[120:123]
	v_mfma_f32_16x16x32_bf16 v[116:119], v[172:175], v[180:183], v[116:119]
	v_mfma_f32_16x16x32_bf16 v[104:107], v[164:167], v[214:217], v[104:107]
	v_mfma_f32_16x16x32_bf16 v[100:103], v[172:175], v[214:217], v[100:103]
	v_mfma_f32_16x16x32_bf16 v[88:91], v[164:167], v[222:225], v[88:91]
	v_mfma_f32_16x16x32_bf16 v[84:87], v[172:175], v[222:225], v[84:87]
	v_mfma_f32_16x16x32_bf16 v[72:75], v[164:167], v[230:233], v[72:75]
	v_mfma_f32_16x16x32_bf16 v[68:71], v[172:175], v[230:233], v[68:71]
	s_setprio 0
	s_barrier
	s_add_i32 s18, s18, s46
	s_mov_b32 m0, s18
	ds_read_b128 v[176:179], v212 offset:16384
	ds_read_b128 v[180:183], v212 offset:17408
	ds_read_b128 v[184:187], v212 offset:18432
	ds_read_b128 v[214:217], v212 offset:19456
	ds_read_b128 v[218:221], v212 offset:20480
	ds_read_b128 v[222:225], v212 offset:21504
	ds_read_b128 v[226:229], v212 offset:22528
	ds_read_b128 v[230:233], v212 offset:23552
	global_load_lds_dwordx4 v2, s[22:23]
	s_add_i32 m0, s18, 0x2000
	s_add_u32 s18, s22, 0xb0000
	s_addc_u32 s19, s23, 0
	s_add_i32 s44, s62, s46
	global_load_lds_dwordx4 v0, s[22:23]
	s_mov_b32 m0, s44
	s_nop 0
	global_load_lds_dwordx4 v2, s[18:19]
	s_add_i32 m0, s44, 0x2000
	s_nop 0
	global_load_lds_dwordx4 v0, s[18:19]
	s_mov_b32 m0, s47
	s_nop 0
	global_load_lds_dwordx4 v2, s[24:25]
	s_mov_b32 m0, s48
	s_nop 0
	global_load_lds_dwordx4 v0, s[24:25]
	s_waitcnt vmcnt(8)
	s_waitcnt lgkmcnt(0)
	s_barrier
	s_setprio 1
	s_waitcnt lgkmcnt(0)
	v_mfma_f32_16x16x32_bf16 v[64:67], v[144:147], v[176:179], v[64:67]
	v_mfma_f32_16x16x32_bf16 v[60:63], v[152:155], v[176:179], v[60:63]
	v_mfma_f32_16x16x32_bf16 v[48:51], v[144:147], v[184:187], v[48:51]
	v_mfma_f32_16x16x32_bf16 v[44:47], v[152:155], v[184:187], v[44:47]
	v_mfma_f32_16x16x32_bf16 v[32:35], v[144:147], v[218:221], v[32:35]
	v_mfma_f32_16x16x32_bf16 v[28:31], v[152:155], v[218:221], v[28:31]
	v_mfma_f32_16x16x32_bf16 v[16:19], v[144:147], v[226:229], v[16:19]
	v_mfma_f32_16x16x32_bf16 v[12:15], v[152:155], v[226:229], v[12:15]
	v_mfma_f32_16x16x32_bf16 v[64:67], v[148:151], v[180:183], v[64:67]
	v_mfma_f32_16x16x32_bf16 v[60:63], v[156:159], v[180:183], v[60:63]
	v_mfma_f32_16x16x32_bf16 v[48:51], v[148:151], v[214:217], v[48:51]
	v_mfma_f32_16x16x32_bf16 v[44:47], v[156:159], v[214:217], v[44:47]
	v_mfma_f32_16x16x32_bf16 v[32:35], v[148:151], v[222:225], v[32:35]
	v_mfma_f32_16x16x32_bf16 v[28:31], v[156:159], v[222:225], v[28:31]
	v_mfma_f32_16x16x32_bf16 v[16:19], v[148:151], v[230:233], v[16:19]
	v_mfma_f32_16x16x32_bf16 v[12:15], v[156:159], v[230:233], v[12:15]
	v_mfma_f32_16x16x32_bf16 v[56:59], v[160:163], v[176:179], v[56:59]
	v_mfma_f32_16x16x32_bf16 v[52:55], v[168:171], v[176:179], v[52:55]
	v_mfma_f32_16x16x32_bf16 v[40:43], v[160:163], v[184:187], v[40:43]
	v_mfma_f32_16x16x32_bf16 v[36:39], v[168:171], v[184:187], v[36:39]
	v_mfma_f32_16x16x32_bf16 v[24:27], v[160:163], v[218:221], v[24:27]
	v_mfma_f32_16x16x32_bf16 v[20:23], v[168:171], v[218:221], v[20:23]
	v_mfma_f32_16x16x32_bf16 v[8:11], v[160:163], v[226:229], v[8:11]
	v_mfma_f32_16x16x32_bf16 v[4:7], v[168:171], v[226:229], v[4:7]
	v_mfma_f32_16x16x32_bf16 v[56:59], v[164:167], v[180:183], v[56:59]
	v_mfma_f32_16x16x32_bf16 v[52:55], v[172:175], v[180:183], v[52:55]
	v_mfma_f32_16x16x32_bf16 v[40:43], v[164:167], v[214:217], v[40:43]
	v_mfma_f32_16x16x32_bf16 v[36:39], v[172:175], v[214:217], v[36:39]
	v_mfma_f32_16x16x32_bf16 v[24:27], v[164:167], v[222:225], v[24:27]
	v_mfma_f32_16x16x32_bf16 v[20:23], v[172:175], v[222:225], v[20:23]
	v_mfma_f32_16x16x32_bf16 v[8:11], v[164:167], v[230:233], v[8:11]
	v_mfma_f32_16x16x32_bf16 v[4:7], v[172:175], v[230:233], v[4:7]
	s_setprio 0
	s_barrier
	s_add_i32 s44, 0, 0x18000
	s_add_i32 s45, 0, 0x1c000
	ds_read_b128 v[144:147], v213 offset:32768
	ds_read_b128 v[148:151], v213 offset:33792
	ds_read_b128 v[152:155], v213 offset:34816
	ds_read_b128 v[156:159], v213 offset:35840
	ds_read_b128 v[160:163], v213 offset:49152
	ds_read_b128 v[164:167], v213 offset:50176
	ds_read_b128 v[168:171], v213 offset:51200
	ds_read_b128 v[172:175], v213 offset:52224
	s_add_u32 s18, s24, 0xb0000
	s_addc_u32 s19, s25, 0
	s_mov_b32 m0, s49
	ds_read_b128 v[176:179], v212 offset:32768
	ds_read_b128 v[180:183], v212 offset:33792
	ds_read_b128 v[184:187], v212 offset:34816
	ds_read_b128 v[214:217], v212 offset:35840
	ds_read_b128 v[218:221], v212 offset:36864
	ds_read_b128 v[222:225], v212 offset:37888
	ds_read_b128 v[226:229], v212 offset:38912
	ds_read_b128 v[230:233], v212 offset:39936
	global_load_lds_dwordx4 v2, s[18:19]
	s_mov_b32 m0, s50
	s_nop 0
	global_load_lds_dwordx4 v0, s[18:19]
	s_waitcnt vmcnt(8)
	s_waitcnt lgkmcnt(0)
	s_barrier
	s_setprio 1
	s_waitcnt lgkmcnt(0)
	v_mfma_f32_16x16x32_bf16 v[128:131], v[144:147], v[176:179], v[128:131]
	v_mfma_f32_16x16x32_bf16 v[124:127], v[152:155], v[176:179], v[124:127]
	v_mfma_f32_16x16x32_bf16 v[112:115], v[144:147], v[184:187], v[112:115]
	v_mfma_f32_16x16x32_bf16 v[108:111], v[152:155], v[184:187], v[108:111]
	v_mfma_f32_16x16x32_bf16 v[96:99], v[144:147], v[218:221], v[96:99]
	v_mfma_f32_16x16x32_bf16 v[92:95], v[152:155], v[218:221], v[92:95]
	v_mfma_f32_16x16x32_bf16 v[80:83], v[144:147], v[226:229], v[80:83]
	v_mfma_f32_16x16x32_bf16 v[76:79], v[152:155], v[226:229], v[76:79]
	v_mfma_f32_16x16x32_bf16 v[128:131], v[148:151], v[180:183], v[128:131]
	v_mfma_f32_16x16x32_bf16 v[124:127], v[156:159], v[180:183], v[124:127]
	v_mfma_f32_16x16x32_bf16 v[112:115], v[148:151], v[214:217], v[112:115]
	v_mfma_f32_16x16x32_bf16 v[108:111], v[156:159], v[214:217], v[108:111]
	v_mfma_f32_16x16x32_bf16 v[96:99], v[148:151], v[222:225], v[96:99]
	v_mfma_f32_16x16x32_bf16 v[92:95], v[156:159], v[222:225], v[92:95]
	v_mfma_f32_16x16x32_bf16 v[80:83], v[148:151], v[230:233], v[80:83]
	v_mfma_f32_16x16x32_bf16 v[76:79], v[156:159], v[230:233], v[76:79]
	v_mfma_f32_16x16x32_bf16 v[120:123], v[160:163], v[176:179], v[120:123]
	v_mfma_f32_16x16x32_bf16 v[116:119], v[168:171], v[176:179], v[116:119]
	v_mfma_f32_16x16x32_bf16 v[104:107], v[160:163], v[184:187], v[104:107]
	v_mfma_f32_16x16x32_bf16 v[100:103], v[168:171], v[184:187], v[100:103]
	v_mfma_f32_16x16x32_bf16 v[88:91], v[160:163], v[218:221], v[88:91]
	v_mfma_f32_16x16x32_bf16 v[84:87], v[168:171], v[218:221], v[84:87]
	v_mfma_f32_16x16x32_bf16 v[72:75], v[160:163], v[226:229], v[72:75]
	v_mfma_f32_16x16x32_bf16 v[68:71], v[168:171], v[226:229], v[68:71]
	v_mfma_f32_16x16x32_bf16 v[120:123], v[164:167], v[180:183], v[120:123]
	v_mfma_f32_16x16x32_bf16 v[116:119], v[172:175], v[180:183], v[116:119]
	v_mfma_f32_16x16x32_bf16 v[104:107], v[164:167], v[214:217], v[104:107]
	v_mfma_f32_16x16x32_bf16 v[100:103], v[172:175], v[214:217], v[100:103]
	v_mfma_f32_16x16x32_bf16 v[88:91], v[164:167], v[222:225], v[88:91]
	v_mfma_f32_16x16x32_bf16 v[84:87], v[172:175], v[222:225], v[84:87]
	v_mfma_f32_16x16x32_bf16 v[72:75], v[164:167], v[230:233], v[72:75]
	v_mfma_f32_16x16x32_bf16 v[68:71], v[172:175], v[230:233], v[68:71]
	s_setprio 0
	s_barrier
	s_add_i32 s18, s44, s46
	s_add_u32 s100, s22, 0x80
	s_addc_u32 s101, s23, 0
	s_mov_b32 m0, s18
	ds_read_b128 v[176:179], v212 offset:49152
	ds_read_b128 v[180:183], v212 offset:50176
	ds_read_b128 v[184:187], v212 offset:51200
	ds_read_b128 v[214:217], v212 offset:52224
	ds_read_b128 v[218:221], v212 offset:53248
	ds_read_b128 v[222:225], v212 offset:54272
	ds_read_b128 v[226:229], v212 offset:55296
	ds_read_b128 v[230:233], v212 offset:56320
	global_load_lds_dwordx4 v2, s[100:101]
	s_add_i32 m0, s18, 0x2000
	s_add_u32 s18, s22, 0xb0080
	s_addc_u32 s19, s23, 0
	s_add_i32 s22, s45, s46
	global_load_lds_dwordx4 v0, s[100:101]
	s_mov_b32 m0, s22
	s_nop 0
	global_load_lds_dwordx4 v2, s[18:19]
	s_add_i32 m0, s22, 0x2000
	s_nop 0
	global_load_lds_dwordx4 v0, s[18:19]
	s_add_u32 s100, s24, 0x80
	s_addc_u32 s101, s25, 0
	s_mov_b32 m0, s52
	s_nop 0
	global_load_lds_dwordx4 v2, s[100:101]
	s_mov_b32 m0, s53
	s_nop 0
	global_load_lds_dwordx4 v0, s[100:101]
	s_waitcnt vmcnt(8)
	s_waitcnt lgkmcnt(0)
	s_barrier
	s_setprio 1
	s_waitcnt lgkmcnt(0)
	v_mfma_f32_16x16x32_bf16 v[64:67], v[144:147], v[176:179], v[64:67]
	v_mfma_f32_16x16x32_bf16 v[60:63], v[152:155], v[176:179], v[60:63]
	v_mfma_f32_16x16x32_bf16 v[48:51], v[144:147], v[184:187], v[48:51]
	v_mfma_f32_16x16x32_bf16 v[44:47], v[152:155], v[184:187], v[44:47]
	v_mfma_f32_16x16x32_bf16 v[32:35], v[144:147], v[218:221], v[32:35]
	v_mfma_f32_16x16x32_bf16 v[28:31], v[152:155], v[218:221], v[28:31]
	v_mfma_f32_16x16x32_bf16 v[16:19], v[144:147], v[226:229], v[16:19]
	v_mfma_f32_16x16x32_bf16 v[12:15], v[152:155], v[226:229], v[12:15]
	v_mfma_f32_16x16x32_bf16 v[64:67], v[148:151], v[180:183], v[64:67]
	v_mfma_f32_16x16x32_bf16 v[60:63], v[156:159], v[180:183], v[60:63]
	v_mfma_f32_16x16x32_bf16 v[48:51], v[148:151], v[214:217], v[48:51]
	v_mfma_f32_16x16x32_bf16 v[44:47], v[156:159], v[214:217], v[44:47]
	v_mfma_f32_16x16x32_bf16 v[32:35], v[148:151], v[222:225], v[32:35]
	v_mfma_f32_16x16x32_bf16 v[28:31], v[156:159], v[222:225], v[28:31]
	v_mfma_f32_16x16x32_bf16 v[16:19], v[148:151], v[230:233], v[16:19]
	v_mfma_f32_16x16x32_bf16 v[12:15], v[156:159], v[230:233], v[12:15]
	v_mfma_f32_16x16x32_bf16 v[56:59], v[160:163], v[176:179], v[56:59]
	v_mfma_f32_16x16x32_bf16 v[52:55], v[168:171], v[176:179], v[52:55]
	v_mfma_f32_16x16x32_bf16 v[40:43], v[160:163], v[184:187], v[40:43]
	v_mfma_f32_16x16x32_bf16 v[36:39], v[168:171], v[184:187], v[36:39]
	v_mfma_f32_16x16x32_bf16 v[24:27], v[160:163], v[218:221], v[24:27]
	v_mfma_f32_16x16x32_bf16 v[20:23], v[168:171], v[218:221], v[20:23]
	v_mfma_f32_16x16x32_bf16 v[8:11], v[160:163], v[226:229], v[8:11]
	v_mfma_f32_16x16x32_bf16 v[4:7], v[168:171], v[226:229], v[4:7]
	v_mfma_f32_16x16x32_bf16 v[56:59], v[164:167], v[180:183], v[56:59]
	v_mfma_f32_16x16x32_bf16 v[52:55], v[172:175], v[180:183], v[52:55]
	v_mfma_f32_16x16x32_bf16 v[40:43], v[164:167], v[214:217], v[40:43]
	v_mfma_f32_16x16x32_bf16 v[36:39], v[172:175], v[214:217], v[36:39]
	v_mfma_f32_16x16x32_bf16 v[24:27], v[164:167], v[222:225], v[24:27]
	v_mfma_f32_16x16x32_bf16 v[20:23], v[172:175], v[222:225], v[20:23]
	v_mfma_f32_16x16x32_bf16 v[8:11], v[164:167], v[230:233], v[8:11]
	v_mfma_f32_16x16x32_bf16 v[4:7], v[172:175], v[230:233], v[4:7]
	s_setprio 0
	s_barrier
	s_add_i32 s15, s15, 2
	s_add_u32 s13, s13, 0x100
	s_addc_u32 s14, s14, 0
	s_cmp_gt_u32 s15, 41
	s_mov_b64 s[44:45], s[42:43]
	s_cbranch_scc0 .LBB0_811
	s_and_b64 vcc, exec, s[4:5]
	s_cbranch_vccz .LBB0_814
	s_barrier

.LBB0_928:
	s_add_u32 s18, s40, 0xfffc0080
	s_addc_u32 s19, s41, -1
	s_add_i32 s52, 0, 0x10000
	s_cmp_eq_u32 s51, 12
	s_cselect_b32 s25, s7, s19
	s_cselect_b32 s24, s13, s18
	s_cselect_b32 s23, s5, s43
	s_cselect_b32 s22, s17, s42
	s_add_i32 s53, 0, 0x14000
	ds_read_b128 v[148:151], v246
	ds_read_b128 v[158:161], v246 offset:1024
	ds_read_b128 v[162:165], v246 offset:2048
	ds_read_b128 v[166:169], v246 offset:3072
	ds_read_b128 v[170:173], v246 offset:16384
	ds_read_b128 v[174:177], v246 offset:17408
	ds_read_b128 v[178:181], v246 offset:18432
	ds_read_b128 v[182:185], v246 offset:19456
	s_add_i32 m0, s29, 0xc000
	ds_read_b128 v[186:189], v157
	ds_read_b128 v[208:211], v157 offset:1024
	ds_read_b128 v[212:215], v157 offset:2048
	ds_read_b128 v[216:219], v157 offset:3072
	ds_read_b128 v[220:223], v157 offset:4096
	ds_read_b128 v[224:227], v157 offset:5120
	ds_read_b128 v[228:231], v157 offset:6144
	ds_read_b128 v[232:235], v157 offset:7168
	global_load_lds_dwordx4 v144, s[40:41]
	s_add_i32 m0, s29, 0xe000
	s_nop 0
	global_load_lds_dwordx4 v146, s[40:41]
	s_waitcnt vmcnt(8)
	s_waitcnt lgkmcnt(0)
	s_barrier
	s_setprio 1
	s_waitcnt lgkmcnt(0)
	v_mfma_f32_16x16x32_bf16 v[128:131], v[148:151], v[186:189], v[128:131]
	v_mfma_f32_16x16x32_bf16 v[124:127], v[162:165], v[186:189], v[124:127]
	v_mfma_f32_16x16x32_bf16 v[116:119], v[148:151], v[212:215], v[116:119]
	v_mfma_f32_16x16x32_bf16 v[108:111], v[162:165], v[212:215], v[108:111]
	v_mfma_f32_16x16x32_bf16 v[100:103], v[148:151], v[220:223], v[100:103]
	v_mfma_f32_16x16x32_bf16 v[92:95], v[162:165], v[220:223], v[92:95]
	v_mfma_f32_16x16x32_bf16 v[84:87], v[148:151], v[228:231], v[84:87]
	v_mfma_f32_16x16x32_bf16 v[76:79], v[162:165], v[228:231], v[76:79]
	v_mfma_f32_16x16x32_bf16 v[128:131], v[158:161], v[208:211], v[128:131]
	v_mfma_f32_16x16x32_bf16 v[124:127], v[166:169], v[208:211], v[124:127]
	v_mfma_f32_16x16x32_bf16 v[116:119], v[158:161], v[216:219], v[116:119]
	v_mfma_f32_16x16x32_bf16 v[108:111], v[166:169], v[216:219], v[108:111]
	v_mfma_f32_16x16x32_bf16 v[100:103], v[158:161], v[224:227], v[100:103]
	v_mfma_f32_16x16x32_bf16 v[92:95], v[166:169], v[224:227], v[92:95]
	v_mfma_f32_16x16x32_bf16 v[84:87], v[158:161], v[232:235], v[84:87]
	v_mfma_f32_16x16x32_bf16 v[76:79], v[166:169], v[232:235], v[76:79]
	v_mfma_f32_16x16x32_bf16 v[120:123], v[170:173], v[186:189], v[120:123]
	v_mfma_f32_16x16x32_bf16 v[112:115], v[178:181], v[186:189], v[112:115]
	v_mfma_f32_16x16x32_bf16 v[104:107], v[170:173], v[212:215], v[104:107]
	v_mfma_f32_16x16x32_bf16 v[96:99], v[178:181], v[212:215], v[96:99]
	v_mfma_f32_16x16x32_bf16 v[88:91], v[170:173], v[220:223], v[88:91]
	v_mfma_f32_16x16x32_bf16 v[80:83], v[178:181], v[220:223], v[80:83]
	v_mfma_f32_16x16x32_bf16 v[72:75], v[170:173], v[228:231], v[72:75]
	v_mfma_f32_16x16x32_bf16 v[68:71], v[178:181], v[228:231], v[68:71]
	v_mfma_f32_16x16x32_bf16 v[120:123], v[174:177], v[208:211], v[120:123]
	v_mfma_f32_16x16x32_bf16 v[112:115], v[182:185], v[208:211], v[112:115]
	v_mfma_f32_16x16x32_bf16 v[104:107], v[174:177], v[216:219], v[104:107]
	v_mfma_f32_16x16x32_bf16 v[96:99], v[182:185], v[216:219], v[96:99]
	v_mfma_f32_16x16x32_bf16 v[88:91], v[174:177], v[224:227], v[88:91]
	v_mfma_f32_16x16x32_bf16 v[80:83], v[182:185], v[224:227], v[80:83]
	v_mfma_f32_16x16x32_bf16 v[72:75], v[174:177], v[232:235], v[72:75]
	v_mfma_f32_16x16x32_bf16 v[68:71], v[182:185], v[232:235], v[68:71]
	s_setprio 0
	s_barrier
	s_add_i32 s18, s52, s28
	s_mov_b32 m0, s18
	ds_read_b128 v[186:189], v157 offset:16384
	ds_read_b128 v[208:211], v157 offset:17408
	ds_read_b128 v[212:215], v157 offset:18432
	ds_read_b128 v[216:219], v157 offset:19456
	ds_read_b128 v[220:223], v157 offset:20480
	ds_read_b128 v[224:227], v157 offset:21504
	ds_read_b128 v[228:231], v157 offset:22528
	ds_read_b128 v[232:235], v157 offset:23552
	global_load_lds_dwordx4 v2, s[22:23]
	s_add_i32 m0, s18, 0x2000
	s_add_u32 s18, s22, 0x10000
	s_addc_u32 s19, s23, 0
	s_add_i32 s52, s53, s28
	global_load_lds_dwordx4 v142, s[22:23]
	s_mov_b32 m0, s52
	s_nop 0
	global_load_lds_dwordx4 v2, s[18:19]
	s_add_i32 m0, s52, 0x2000
	s_nop 0
	global_load_lds_dwordx4 v142, s[18:19]
	s_mov_b32 m0, s29
	s_nop 0
	global_load_lds_dwordx4 v0, s[24:25]
	s_mov_b32 m0, s44
	s_nop 0
	global_load_lds_dwordx4 v140, s[24:25]
	s_waitcnt vmcnt(8)
	s_waitcnt lgkmcnt(0)
	s_barrier
	s_setprio 1
	s_waitcnt lgkmcnt(0)
	v_mfma_f32_16x16x32_bf16 v[64:67], v[148:151], v[186:189], v[64:67]
	v_mfma_f32_16x16x32_bf16 v[60:63], v[162:165], v[186:189], v[60:63]
	v_mfma_f32_16x16x32_bf16 v[52:55], v[148:151], v[212:215], v[52:55]
	v_mfma_f32_16x16x32_bf16 v[44:47], v[162:165], v[212:215], v[44:47]
	v_mfma_f32_16x16x32_bf16 v[36:39], v[148:151], v[220:223], v[36:39]
	v_mfma_f32_16x16x32_bf16 v[28:31], v[162:165], v[220:223], v[28:31]
	v_mfma_f32_16x16x32_bf16 v[20:23], v[148:151], v[228:231], v[20:23]
	v_mfma_f32_16x16x32_bf16 v[12:15], v[162:165], v[228:231], v[12:15]
	v_mfma_f32_16x16x32_bf16 v[64:67], v[158:161], v[208:211], v[64:67]
	v_mfma_f32_16x16x32_bf16 v[60:63], v[166:169], v[208:211], v[60:63]
	v_mfma_f32_16x16x32_bf16 v[52:55], v[158:161], v[216:219], v[52:55]
	v_mfma_f32_16x16x32_bf16 v[44:47], v[166:169], v[216:219], v[44:47]
	v_mfma_f32_16x16x32_bf16 v[36:39], v[158:161], v[224:227], v[36:39]
	v_mfma_f32_16x16x32_bf16 v[28:31], v[166:169], v[224:227], v[28:31]
	v_mfma_f32_16x16x32_bf16 v[20:23], v[158:161], v[232:235], v[20:23]
	v_mfma_f32_16x16x32_bf16 v[12:15], v[166:169], v[232:235], v[12:15]
	v_mfma_f32_16x16x32_bf16 v[56:59], v[170:173], v[186:189], v[56:59]
	v_mfma_f32_16x16x32_bf16 v[48:51], v[178:181], v[186:189], v[48:51]
	v_mfma_f32_16x16x32_bf16 v[40:43], v[170:173], v[212:215], v[40:43]
	v_mfma_f32_16x16x32_bf16 v[32:35], v[178:181], v[212:215], v[32:35]
	v_mfma_f32_16x16x32_bf16 v[24:27], v[170:173], v[220:223], v[24:27]
	v_mfma_f32_16x16x32_bf16 v[16:19], v[178:181], v[220:223], v[16:19]
	v_mfma_f32_16x16x32_bf16 v[8:11], v[170:173], v[228:231], v[8:11]
	v_mfma_f32_16x16x32_bf16 v[4:7], v[178:181], v[228:231], v[4:7]
	v_mfma_f32_16x16x32_bf16 v[56:59], v[174:177], v[208:211], v[56:59]
	v_mfma_f32_16x16x32_bf16 v[48:51], v[182:185], v[208:211], v[48:51]
	v_mfma_f32_16x16x32_bf16 v[40:43], v[174:177], v[216:219], v[40:43]
	v_mfma_f32_16x16x32_bf16 v[32:35], v[182:185], v[216:219], v[32:35]
	v_mfma_f32_16x16x32_bf16 v[24:27], v[174:177], v[224:227], v[24:27]
	v_mfma_f32_16x16x32_bf16 v[16:19], v[182:185], v[224:227], v[16:19]
	v_mfma_f32_16x16x32_bf16 v[8:11], v[174:177], v[232:235], v[8:11]
	v_mfma_f32_16x16x32_bf16 v[4:7], v[182:185], v[232:235], v[4:7]
	s_setprio 0
	s_barrier
	s_add_i32 s52, 0, 0x18000
	s_add_i32 s53, 0, 0x1c000
	ds_read_b128 v[148:151], v246 offset:32768
	ds_read_b128 v[158:161], v246 offset:33792
	ds_read_b128 v[162:165], v246 offset:34816
	ds_read_b128 v[166:169], v246 offset:35840
	ds_read_b128 v[170:173], v246 offset:49152
	ds_read_b128 v[174:177], v246 offset:50176
	ds_read_b128 v[178:181], v246 offset:51200
	ds_read_b128 v[182:185], v246 offset:52224
	s_add_u32 s18, s24, 0x40000
	s_addc_u32 s19, s25, 0
	s_mov_b32 m0, s45
	ds_read_b128 v[186:189], v157 offset:32768
	ds_read_b128 v[208:211], v157 offset:33792
	ds_read_b128 v[212:215], v157 offset:34816
	ds_read_b128 v[216:219], v157 offset:35840
	ds_read_b128 v[220:223], v157 offset:36864
	ds_read_b128 v[224:227], v157 offset:37888
	ds_read_b128 v[228:231], v157 offset:38912
	ds_read_b128 v[232:235], v157 offset:39936
	global_load_lds_dwordx4 v0, s[18:19]
	s_mov_b32 m0, s46
	s_nop 0
	global_load_lds_dwordx4 v140, s[18:19]
	s_waitcnt vmcnt(8)
	s_waitcnt lgkmcnt(0)
	s_barrier
	s_setprio 1
	s_waitcnt lgkmcnt(0)
	v_mfma_f32_16x16x32_bf16 v[128:131], v[148:151], v[186:189], v[128:131]
	v_mfma_f32_16x16x32_bf16 v[124:127], v[162:165], v[186:189], v[124:127]
	v_mfma_f32_16x16x32_bf16 v[116:119], v[148:151], v[212:215], v[116:119]
	v_mfma_f32_16x16x32_bf16 v[108:111], v[162:165], v[212:215], v[108:111]
	v_mfma_f32_16x16x32_bf16 v[100:103], v[148:151], v[220:223], v[100:103]
	v_mfma_f32_16x16x32_bf16 v[92:95], v[162:165], v[220:223], v[92:95]
	v_mfma_f32_16x16x32_bf16 v[84:87], v[148:151], v[228:231], v[84:87]
	v_mfma_f32_16x16x32_bf16 v[76:79], v[162:165], v[228:231], v[76:79]
	v_mfma_f32_16x16x32_bf16 v[128:131], v[158:161], v[208:211], v[128:131]
	v_mfma_f32_16x16x32_bf16 v[124:127], v[166:169], v[208:211], v[124:127]
	v_mfma_f32_16x16x32_bf16 v[116:119], v[158:161], v[216:219], v[116:119]
	v_mfma_f32_16x16x32_bf16 v[108:111], v[166:169], v[216:219], v[108:111]
	v_mfma_f32_16x16x32_bf16 v[100:103], v[158:161], v[224:227], v[100:103]
	v_mfma_f32_16x16x32_bf16 v[92:95], v[166:169], v[224:227], v[92:95]
	v_mfma_f32_16x16x32_bf16 v[84:87], v[158:161], v[232:235], v[84:87]
	v_mfma_f32_16x16x32_bf16 v[76:79], v[166:169], v[232:235], v[76:79]
	v_mfma_f32_16x16x32_bf16 v[120:123], v[170:173], v[186:189], v[120:123]
	v_mfma_f32_16x16x32_bf16 v[112:115], v[178:181], v[186:189], v[112:115]
	v_mfma_f32_16x16x32_bf16 v[104:107], v[170:173], v[212:215], v[104:107]
	v_mfma_f32_16x16x32_bf16 v[96:99], v[178:181], v[212:215], v[96:99]
	v_mfma_f32_16x16x32_bf16 v[88:91], v[170:173], v[220:223], v[88:91]
	v_mfma_f32_16x16x32_bf16 v[80:83], v[178:181], v[220:223], v[80:83]
	v_mfma_f32_16x16x32_bf16 v[72:75], v[170:173], v[228:231], v[72:75]
	v_mfma_f32_16x16x32_bf16 v[68:71], v[178:181], v[228:231], v[68:71]
	v_mfma_f32_16x16x32_bf16 v[120:123], v[174:177], v[208:211], v[120:123]
	v_mfma_f32_16x16x32_bf16 v[112:115], v[182:185], v[208:211], v[112:115]
	v_mfma_f32_16x16x32_bf16 v[104:107], v[174:177], v[216:219], v[104:107]
	v_mfma_f32_16x16x32_bf16 v[96:99], v[182:185], v[216:219], v[96:99]
	v_mfma_f32_16x16x32_bf16 v[88:91], v[174:177], v[224:227], v[88:91]
	v_mfma_f32_16x16x32_bf16 v[80:83], v[182:185], v[224:227], v[80:83]
	v_mfma_f32_16x16x32_bf16 v[72:75], v[174:177], v[232:235], v[72:75]
	v_mfma_f32_16x16x32_bf16 v[68:71], v[182:185], v[232:235], v[68:71]
	s_setprio 0
	s_barrier
	s_add_i32 s18, s52, s28
	s_add_u32 s100, s22, 0x80
	s_addc_u32 s101, s23, 0
	s_mov_b32 m0, s18
	ds_read_b128 v[186:189], v157 offset:49152
	ds_read_b128 v[208:211], v157 offset:50176
	ds_read_b128 v[212:215], v157 offset:51200
	ds_read_b128 v[216:219], v157 offset:52224
	ds_read_b128 v[220:223], v157 offset:53248
	ds_read_b128 v[224:227], v157 offset:54272
	ds_read_b128 v[228:231], v157 offset:55296
	ds_read_b128 v[232:235], v157 offset:56320
	global_load_lds_dwordx4 v2, s[100:101]
	s_add_i32 m0, s18, 0x2000
	s_add_u32 s18, s22, 0x10080
	s_addc_u32 s19, s23, 0
	s_add_i32 s22, s53, s28
	global_load_lds_dwordx4 v142, s[100:101]
	s_mov_b32 m0, s22
	s_nop 0
	global_load_lds_dwordx4 v2, s[18:19]
	s_add_i32 m0, s22, 0x2000
	s_nop 0
	global_load_lds_dwordx4 v142, s[18:19]
	s_add_u32 s100, s24, 0x80
	s_addc_u32 s101, s25, 0
	s_mov_b32 m0, s47
	s_nop 0
	global_load_lds_dwordx4 v0, s[100:101]
	s_mov_b32 m0, s48
	s_nop 0
	global_load_lds_dwordx4 v140, s[100:101]
	s_waitcnt vmcnt(8)
	s_waitcnt lgkmcnt(0)
	s_barrier
	s_setprio 1
	s_waitcnt lgkmcnt(0)
	v_mfma_f32_16x16x32_bf16 v[64:67], v[148:151], v[186:189], v[64:67]
	v_mfma_f32_16x16x32_bf16 v[60:63], v[162:165], v[186:189], v[60:63]
	v_mfma_f32_16x16x32_bf16 v[52:55], v[148:151], v[212:215], v[52:55]
	v_mfma_f32_16x16x32_bf16 v[44:47], v[162:165], v[212:215], v[44:47]
	v_mfma_f32_16x16x32_bf16 v[36:39], v[148:151], v[220:223], v[36:39]
	v_mfma_f32_16x16x32_bf16 v[28:31], v[162:165], v[220:223], v[28:31]
	v_mfma_f32_16x16x32_bf16 v[20:23], v[148:151], v[228:231], v[20:23]
	v_mfma_f32_16x16x32_bf16 v[12:15], v[162:165], v[228:231], v[12:15]
	v_mfma_f32_16x16x32_bf16 v[64:67], v[158:161], v[208:211], v[64:67]
	v_mfma_f32_16x16x32_bf16 v[60:63], v[166:169], v[208:211], v[60:63]
	v_mfma_f32_16x16x32_bf16 v[52:55], v[158:161], v[216:219], v[52:55]
	v_mfma_f32_16x16x32_bf16 v[44:47], v[166:169], v[216:219], v[44:47]
	v_mfma_f32_16x16x32_bf16 v[36:39], v[158:161], v[224:227], v[36:39]
	v_mfma_f32_16x16x32_bf16 v[28:31], v[166:169], v[224:227], v[28:31]
	v_mfma_f32_16x16x32_bf16 v[20:23], v[158:161], v[232:235], v[20:23]
	v_mfma_f32_16x16x32_bf16 v[12:15], v[166:169], v[232:235], v[12:15]
	v_mfma_f32_16x16x32_bf16 v[56:59], v[170:173], v[186:189], v[56:59]
	v_mfma_f32_16x16x32_bf16 v[48:51], v[178:181], v[186:189], v[48:51]
	v_mfma_f32_16x16x32_bf16 v[40:43], v[170:173], v[212:215], v[40:43]
	v_mfma_f32_16x16x32_bf16 v[32:35], v[178:181], v[212:215], v[32:35]
	v_mfma_f32_16x16x32_bf16 v[24:27], v[170:173], v[220:223], v[24:27]
	v_mfma_f32_16x16x32_bf16 v[16:19], v[178:181], v[220:223], v[16:19]
	v_mfma_f32_16x16x32_bf16 v[8:11], v[170:173], v[228:231], v[8:11]
	v_mfma_f32_16x16x32_bf16 v[4:7], v[178:181], v[228:231], v[4:7]
	v_mfma_f32_16x16x32_bf16 v[56:59], v[174:177], v[208:211], v[56:59]
	v_mfma_f32_16x16x32_bf16 v[48:51], v[182:185], v[208:211], v[48:51]
	v_mfma_f32_16x16x32_bf16 v[40:43], v[174:177], v[216:219], v[40:43]
	v_mfma_f32_16x16x32_bf16 v[32:35], v[182:185], v[216:219], v[32:35]
	v_mfma_f32_16x16x32_bf16 v[24:27], v[174:177], v[224:227], v[24:27]
	v_mfma_f32_16x16x32_bf16 v[16:19], v[182:185], v[224:227], v[16:19]
	v_mfma_f32_16x16x32_bf16 v[8:11], v[174:177], v[232:235], v[8:11]
	v_mfma_f32_16x16x32_bf16 v[4:7], v[182:185], v[232:235], v[4:7]
	s_setprio 0
	s_barrier
	s_add_i32 s51, s51, 2
	s_add_u32 s40, s40, 0x100
	s_addc_u32 s41, s41, 0
	s_add_u32 s42, s42, 0x100
	s_addc_u32 s43, s43, 0
	s_cmp_gt_u32 s51, 13
	s_cbranch_scc0 .LBB0_928
	s_lshl_b32 s5, s16, 8
	s_and_b64 vcc, exec, s[2:3]
	s_cbranch_vccz .LBB0_931
	v_or_b32_e32 v148, s5, v154
	v_ashrrev_i32_e32 v149, 31, v148
	v_lshlrev_b64 v[148:149], 6, v[148:149]
	v_lshl_add_u64 v[166:167], s[74:75], 0, v[148:149]
	global_load_dwordx4 v[148:151], v[166:167], off
	global_load_dwordx4 v[158:161], v[166:167], off offset:32
	global_load_dwordx4 v[162:165], v[166:167], off offset:16
	s_nop 0
	global_load_dwordx4 v[166:169], v[166:167], off offset:48
	s_barrier
